# c21 + direct slot polling also in the last-layer f32 fused-LN epilogue (all three copies now poll the slots directly)
# speedup vs baseline: 1.0064x; 1.0007x over previous
;     __device__ __forceinline__ void fused(AccT& acc, const Unit& u, int wr, int wc, int fr_in, int fq_in, LAS unsigned char* lds, int wid, int lane_in) const {
;     ...
;         asm volatile("s_waitcnt vmcnt(0)" ::: "memory");
;         if (lane == 0) __hip_atomic_fetch_add(cnt + 64 * u.pm, 1u, __ATOMIC_RELAXED, __HIP_MEMORY_SCOPE_AGENT);
.LBB0_1312:
	s_or_b64 exec, exec, s[18:19]
	v_cmp_eq_u32_e64 s[38:39], 0, v207
	s_and_saveexec_b64 s[16:17], s[38:39]
	s_cbranch_execz .LBB0_1315
	s_mov_b64 s[18:19], exec
	v_mbcnt_lo_u32_b32 v130, s18, 0
	v_mbcnt_hi_u32_b32 v130, s19, v130
	v_cmp_eq_u32_e32 vcc, 0, v130
	s_and_b64 s[0:1], exec, vcc
	s_mov_b64 exec, s[0:1]
	s_cbranch_execz .LBB0_1315
	s_lshl_b32 s0, s51, 6
	s_ashr_i32 s1, s0, 31
	s_lshl_b64 s[0:1], s[0:1], 2
	v_readlane_b32 s2, v253, 11
	s_add_u32 s0, s2, s0
	v_readlane_b32 s2, v253, 12
	s_addc_u32 s1, s2, s1
	s_bcnt1_i32_b64 s2, s[18:19]
	v_mov_b32_e32 v130, s2
	global_atomic_add v131, v130, s[0:1]

;     __device__ __forceinline__ void fused(AccT& acc, const Unit& u, int wr, int wc, int fr_in, int fq_in, LAS unsigned char* lds, int wid, int lane_in) const {
;     ...
;         if (wid == 0) {
;             unsigned sp = 0;
;             while ((unsigned)__builtin_amdgcn_readfirstlane(__hip_atomic_load(cnt + 64 * u.pm, __ATOMIC_RELAXED, __HIP_MEMORY_SCOPE_AGENT)) < want) {
;                 __builtin_amdgcn_s_sleep(1);
;                 if ((++sp & 1023u) == 0u) { if (__builtin_amdgcn_readfirstlane(__hip_atomic_load(tmo, __ATOMIC_RELAXED, __HIP_MEMORY_SCOPE_AGENT)) != 0u) break;
;                     if (sp > (1u << 22)) { if (lane == 0) __hip_atomic_store(tmo, 1u, __ATOMIC_RELAXED, __HIP_MEMORY_SCOPE_AGENT); break; } } }
;             __builtin_amdgcn_fence(__ATOMIC_ACQUIRE, "agent");
;         }
;         asm volatile("s_waitcnt vmcnt(0) lgkmcnt(0)" ::: "memory"); __builtin_amdgcn_s_barrier(); asm volatile("" ::: "memory");
;         if (lane < 32) {
;             const unsigned long long* slot = xbuf + (size_t)(u.pm * BM + row) * 8; float mt[8], m2[8]; float ms = 0.f;
; #pragma unroll
;             for (int t = 0; t < 8; ++t) { const unsigned long long w = __hip_atomic_load(slot + t, __ATOMIC_RELAXED, __HIP_MEMORY_SCOPE_AGENT); mt[t] = __uint_as_float((unsigned)w); m2[t] = __uint_as_float((unsigned)(w >> 32)); ms += mt[t]; }
;             const float mean = ms * 0.125f; float q = 0.f;
; #pragma unroll
;             for (int t = 0; t < 8; ++t) { const float dm = mt[t] - mean; q += m2[t] + 256.0f * dm * dm; }
;             S[row] = (f32x2){mean, rsqrtf(q * (1.0f / 2048.0f) + LN_EPS)};
.LBB0_1330:
	s_and_saveexec_b64 s[16:17], s[36:37]
	s_cbranch_execz .LBB0_1332
	v_readlane_b32 s0, v253, 9
	v_lshlrev_b64 v[166:167], 6, v[166:167]
	v_readlane_b32 s1, v253, 10
	v_lshl_add_u32 v1, v1, 3, 0
	s_nop 0
	v_lshl_add_u64 v[166:167], s[0:1], 0, v[166:167]
	s_mov_b32 s2, 0
.Lxp2_retry:
	global_load_dwordx2 v[168:169], v[166:167], off sc1
	global_load_dwordx2 v[170:171], v[166:167], off offset:8 sc1
	global_load_dwordx2 v[172:173], v[166:167], off offset:16 sc1
	global_load_dwordx2 v[174:175], v[166:167], off offset:24 sc1
	global_load_dwordx2 v[176:177], v[166:167], off offset:32 sc1
	global_load_dwordx2 v[178:179], v[166:167], off offset:40 sc1
	global_load_dwordx2 v[180:181], v[166:167], off offset:48 sc1
	global_load_dwordx2 v[182:183], v[166:167], off offset:56 sc1
	s_waitcnt vmcnt(0)
	v_or_b32_e32 v130, v169, v171
	v_or_b32_e32 v130, v130, v173
	v_or_b32_e32 v130, v130, v175
	v_or_b32_e32 v130, v130, v177
	v_or_b32_e32 v130, v130, v179
	v_or_b32_e32 v130, v130, v181
	v_or_b32_e32 v130, v130, v183
	v_cmp_le_i32_e32 vcc, 0, v130
	s_nop 4
	s_andn2_b64 vcc, exec, vcc
	s_cbranch_scc0 .Lxp2_done
	s_sleep 1
	s_add_i32 s2, s2, 1
	s_cmp_lt_u32 s2, 0x2000
	s_cbranch_scc1 .Lxp2_retry
.Lxp2_done:
	v_mov_b32_e32 v166, v182
	v_mov_b32_e32 v167, v183
	v_add_f32_e32 v130, 0, v168
	v_add_f32_e32 v130, v130, v170
	v_add_f32_e32 v130, v130, v172
	v_add_f32_e32 v130, v130, v174
	v_add_f32_e32 v130, v130, v176
	v_add_f32_e32 v130, v130, v178
	v_add_f32_e32 v130, v130, v180
	v_add_f32_e32 v130, v130, v166
	v_fmamk_f32 v168, v130, 0xbe000000, v168
	v_mul_f32_e32 v183, 0x43800000, v168
	v_fmac_f32_e32 v169, v168, v183
	v_add_f32_e32 v168, 0, v169
	v_fmamk_f32 v169, v130, 0xbe000000, v170
	v_mul_f32_e32 v170, 0x43800000, v169
	v_fmac_f32_e32 v171, v169, v170
	v_fmamk_f32 v169, v130, 0xbe000000, v172
	v_mul_f32_e32 v170, 0x43800000, v169
	v_fmac_f32_e32 v173, v169, v170
	v_fmamk_f32 v169, v130, 0xbe000000, v174
	v_mul_f32_e32 v170, 0x43800000, v169
	v_fmac_f32_e32 v175, v169, v170
	v_fmamk_f32 v169, v130, 0xbe000000, v176
	v_mul_f32_e32 v170, 0x43800000, v169
	v_add_f32_e32 v168, v171, v168
	v_fmac_f32_e32 v177, v169, v170
	v_fmamk_f32 v169, v130, 0xbe000000, v178
	v_add_f32_e32 v168, v173, v168
	v_mul_f32_e32 v170, 0x43800000, v169
	v_add_f32_e32 v168, v175, v168
	v_fmac_f32_e32 v179, v169, v170
	v_fmamk_f32 v169, v130, 0xbe000000, v180
	v_mul_f32_e32 v182, 0x3e000000, v130
	v_add_f32_e32 v168, v177, v168
	v_mul_f32_e32 v170, 0x43800000, v169
	v_fmamk_f32 v130, v130, 0xbe000000, v166
	v_add_f32_e32 v168, v179, v168
	v_fmac_f32_e32 v181, v169, v170
	v_mul_f32_e32 v166, 0x43800000, v130
	v_add_f32_e32 v168, v181, v168
	v_fmac_f32_e32 v167, v130, v166
	v_add_f32_e32 v130, v167, v168
	v_fmamk_f32 v130, v130, 0x3a000000, v226
	v_cmp_gt_f32_e32 vcc, s15, v130
	v_mul_f32_e32 v166, 0x4b800000, v130
	s_nop 0
	v_cndmask_b32_e32 v130, v130, v166, vcc
	v_rsq_f32_e32 v130, v130
	s_nop 0
	v_mul_f32_e32 v166, 0x45800000, v130
	v_cndmask_b32_e32 v183, v130, v166, vcc
	ds_write_b64 v1, v[182:183] offset:8192
